# v18 + nt on pure streaming loads (merge/LN/conv rows); conv weight vectors and halo rows keep normal caching
# speedup vs baseline: 1.0077x; 1.0040x over previous
; DI void phase_conv(const Params& p, int layer, int ntok, int S, int tid) {
;     ...
;         for (int i = 0; i < SEG; ++i) { rv[i + 1] = *(const u32x2*)(hv + (size_t)i * NUP); rg[i + 1] = *(const u32x2*)(hg + (size_t)i * NUP); }
;         { const bool hn = (pos0 + SEG - 1) < S - 1; rv[SEG + 1] = hn ? *(const u32x2*)(hv + (size_t)SEG * NUP) : z; rg[SEG + 1] = hn ? *(const u32x2*)(hg + (size_t)SEG * NUP) : z; }
.LBB0_221:
	s_or_b64 exec, exec, s[0:1]
	v_add_co_u32_e32 v38, vcc, 0x1000, v100
	s_mov_b32 s0, 0x10000
	s_nop 0
	v_addc_co_u32_e32 v39, vcc, 0, v101, vcc
	v_add_co_u32_e32 v40, vcc, 0x2000, v100
	s_nop 1
	v_addc_co_u32_e32 v41, vcc, 0, v101, vcc
	v_add_co_u32_e32 v42, vcc, 0x4000, v100
	s_nop 1
	v_addc_co_u32_e32 v43, vcc, 0, v101, vcc
	global_load_dwordx2 v[108:109], v[100:101], off nt
	global_load_dwordx2 v[102:103], v[38:39], off offset:1536 nt
	global_load_dwordx2 v[106:107], v[40:41], off offset:3072 nt
	global_load_dwordx2 v[104:105], v[42:43], off offset:512 nt
	v_add_co_u32_e32 v38, vcc, 0x5000, v100
	s_nop 1
	v_addc_co_u32_e32 v39, vcc, 0, v101, vcc
	v_add_co_u32_e32 v40, vcc, 0x6000, v100
	s_nop 1
	v_addc_co_u32_e32 v41, vcc, 0, v101, vcc
	v_add_co_u32_e32 v42, vcc, 0x8000, v100
	s_nop 1
	v_addc_co_u32_e32 v43, vcc, 0, v101, vcc
	v_add_co_u32_e32 v44, vcc, 0x9000, v100
	s_nop 1
	v_addc_co_u32_e32 v45, vcc, 0, v101, vcc
	global_load_dwordx2 v[94:95], v[38:39], off offset:2048 nt
	global_load_dwordx2 v[92:93], v[40:41], off offset:3584 nt
	global_load_dwordx2 v[90:91], v[42:43], off offset:1024 nt
	global_load_dwordx2 v[88:89], v[44:45], off offset:2560 nt
	v_add_co_u32_e32 v38, vcc, 0xb000, v100
	s_nop 1
	v_addc_co_u32_e32 v39, vcc, 0, v101, vcc
	v_add_co_u32_e32 v40, vcc, 0xc000, v100
	s_nop 1
	v_addc_co_u32_e32 v41, vcc, 0, v101, vcc
	v_add_co_u32_e32 v42, vcc, 0xd000, v100
	s_nop 1
	v_addc_co_u32_e32 v43, vcc, 0, v101, vcc
	v_add_co_u32_e32 v44, vcc, 0xf000, v100
	s_nop 1
	v_addc_co_u32_e32 v45, vcc, 0, v101, vcc
	global_load_dwordx2 v[86:87], v[38:39], off nt
	global_load_dwordx2 v[84:85], v[40:41], off offset:1536 nt
	global_load_dwordx2 v[82:83], v[42:43], off offset:3072 nt
	global_load_dwordx2 v[80:81], v[44:45], off offset:512 nt
	v_add_co_u32_e32 v38, vcc, s0, v100
	s_mov_b32 s0, 0x14000
	s_nop 0
	v_addc_co_u32_e32 v39, vcc, 0, v101, vcc
	v_add_co_u32_e32 v40, vcc, 0x11000, v100
	s_nop 1
	v_addc_co_u32_e32 v41, vcc, 0, v101, vcc
	v_add_co_u32_e32 v42, vcc, 0x13000, v100
	s_nop 1
	v_addc_co_u32_e32 v43, vcc, 0, v101, vcc
	v_add_co_u32_e32 v44, vcc, s0, v100
	s_mov_b32 s0, 0x16000
	s_nop 0
	v_addc_co_u32_e32 v45, vcc, 0, v101, vcc
	global_load_dwordx2 v[78:79], v[38:39], off offset:2048 nt
	global_load_dwordx2 v[76:77], v[40:41], off offset:3584 nt
	global_load_dwordx2 v[74:75], v[42:43], off offset:1024 nt
	global_load_dwordx2 v[72:73], v[44:45], off offset:2560 nt
	v_add_co_u32_e32 v38, vcc, s0, v100
	s_mov_b32 s0, 0x18000
	s_nop 0
	v_addc_co_u32_e32 v39, vcc, 0, v101, vcc
	v_add_co_u32_e32 v40, vcc, 0x17000, v100
	s_nop 1
	v_addc_co_u32_e32 v41, vcc, 0, v101, vcc
	v_add_co_u32_e32 v42, vcc, s0, v100
	s_mov_b32 s0, 0x1a000
	s_nop 0
	v_addc_co_u32_e32 v43, vcc, 0, v101, vcc
	v_add_co_u32_e32 v44, vcc, s0, v100
	s_mov_b32 s0, 0x1c000
	s_nop 0
	v_addc_co_u32_e32 v45, vcc, 0, v101, vcc
	global_load_dwordx2 v[70:71], v[38:39], off nt
	global_load_dwordx2 v[68:69], v[40:41], off offset:1536 nt
	global_load_dwordx2 v[66:67], v[42:43], off offset:3072 nt
	global_load_dwordx2 v[64:65], v[44:45], off offset:512 nt
	v_add_co_u32_e32 v38, vcc, 0x1b000, v100
	s_nop 1
	v_addc_co_u32_e32 v39, vcc, 0, v101, vcc
	v_add_co_u32_e32 v40, vcc, s0, v100
	s_mov_b32 s0, 0x1e000
	s_nop 0
	v_addc_co_u32_e32 v41, vcc, 0, v101, vcc
	v_add_co_u32_e32 v42, vcc, s0, v100
	s_nop 1
	v_addc_co_u32_e32 v43, vcc, 0, v101, vcc
	v_add_co_u32_e32 v44, vcc, 0x1f000, v100
	s_nop 1
	v_addc_co_u32_e32 v45, vcc, 0, v101, vcc
	global_load_dwordx2 v[62:63], v[38:39], off offset:2048 nt
	global_load_dwordx2 v[60:61], v[40:41], off offset:3584 nt
	global_load_dwordx2 v[58:59], v[42:43], off offset:1024 nt
	global_load_dwordx2 v[56:57], v[44:45], off offset:2560 nt
	v_add_co_u32_e32 v38, vcc, 0x21000, v100
	s_nop 1
	v_addc_co_u32_e32 v39, vcc, 0, v101, vcc
	v_add_co_u32_e32 v40, vcc, 0x22000, v100
	s_nop 1
	v_addc_co_u32_e32 v41, vcc, 0, v101, vcc
	v_add_co_u32_e32 v42, vcc, 0x23000, v100
	s_nop 1
	v_addc_co_u32_e32 v43, vcc, 0, v101, vcc
	v_add_co_u32_e32 v44, vcc, 0x25000, v100
	s_nop 1
	v_addc_co_u32_e32 v45, vcc, 0, v101, vcc
	global_load_dwordx2 v[54:55], v[38:39], off nt
	global_load_dwordx2 v[52:53], v[40:41], off offset:1536 nt
	global_load_dwordx2 v[50:51], v[42:43], off offset:3072 nt
	global_load_dwordx2 v[48:49], v[44:45], off offset:512 nt
	v_add_co_u32_e32 v38, vcc, 0x26000, v100
	s_nop 1
	v_addc_co_u32_e32 v39, vcc, 0, v101, vcc
	v_add_co_u32_e32 v40, vcc, 0x27000, v100
	s_nop 1
	v_addc_co_u32_e32 v41, vcc, 0, v101, vcc
	v_add_co_u32_e32 v42, vcc, 0x29000, v100
	s_nop 1
	v_addc_co_u32_e32 v43, vcc, 0, v101, vcc
	v_add_co_u32_e32 v114, vcc, 0x2a000, v100
	s_nop 1
	v_addc_co_u32_e32 v115, vcc, 0, v101, vcc
	global_load_dwordx2 v[46:47], v[38:39], off offset:2048 nt
	global_load_dwordx2 v[44:45], v[40:41], off offset:3584 nt
	s_nop 0
	global_load_dwordx2 v[42:43], v[42:43], off offset:1024 nt
	s_nop 0
	global_load_dwordx2 v[40:41], v[114:115], off offset:2560 nt
	v_cmp_gt_i32_e32 vcc, s7, v35
	v_mov_b32_e32 v35, 0
	v_mov_b32_e32 v38, 0
	v_mov_b32_e32 v39, 0
	s_and_saveexec_b64 s[0:1], vcc
	s_cbranch_execz .LBB0_218
	v_add_co_u32_e32 v34, vcc, 0x2c000, v100
	s_nop 1
	v_addc_co_u32_e32 v35, vcc, 0, v101, vcc
	v_add_co_u32_e32 v38, vcc, 0x2d000, v100
	s_nop 1
	v_addc_co_u32_e32 v39, vcc, 0, v101, vcc
	global_load_dwordx2 v[34:35], v[34:35], off
	s_nop 0
	global_load_dwordx2 v[38:39], v[38:39], off offset:1536
	s_branch .LBB0_218
